# diff loops: K/V tile LDS writes for the next pair moved from the loop header into the tail of the previous iteration body (write latency hidden before the barrier) (measurement 1)
# speedup vs baseline: 1.0046x; 1.0006x over previous
.Lnoprio_925:
	s_movk_i32 s99, 0x4800
	v_lshlrev_b32_e32 v136, 1, v160
	s_barrier
	s_waitcnt vmcnt(3)
	ds_write_b128 v244, v[18:21]
	s_waitcnt vmcnt(1)
	ds_write_b128 v245, v[22:25] offset:32768
	s_waitcnt vmcnt(1)
	ds_write_b128 v244, v[26:29] offset:8192
	s_waitcnt vmcnt(0)
	ds_write_b128 v245, v[30:33] offset:41984
	v_xor_b32_e32 v244, 0x4000, v244
	v_add_u32_e32 v245, 0x4800, v245
	s_branch .LBB0_926
.LBB0_925:
	s_waitcnt lgkmcnt(1)
	v_mfma_f32_16x16x32_bf16 v[172:175], v[130:133], v[34:37], v[2:5]
	ds_read_b128 v[184:187], v247 offset:2048
	v_mfma_f32_16x16x32_bf16 v[180:183], v[130:133], v[38:41], v[10:13]
	ds_read_b128 v[130:133], v247
	s_nop 2
	s_nop 1
	v_exp_f32_e32 v200, v172
	v_exp_f32_e32 v201, v175
	s_waitcnt lgkmcnt(2)
	v_mfma_f32_16x16x32_bf16 v[176:179], v[168:171], v[34:37], v[2:5]
	v_exp_f32_e32 v180, v180
	ds_read_b64 v[216:217], v248 offset:37376
	ds_read_b64 v[218:219], v248 offset:37408
	v_mfma_f32_16x16x32_bf16 v[168:171], v[168:171], v[38:41], v[10:13]
	ds_read_b64 v[220:221], v248 offset:39680
	ds_read_b64 v[222:223], v248 offset:39712
	s_nop 2
	v_exp_f32_e32 v204, v176
	v_exp_f32_e32 v176, v173
	s_waitcnt lgkmcnt(4)
	v_mfma_f32_16x16x32_bf16 v[188:191], v[130:133], v[42:45], v[6:9]
	v_exp_f32_e32 v205, v177
	v_exp_f32_e32 v213, v168
	v_exp_f32_e32 v168, v181
	v_mfma_f32_16x16x32_bf16 v[196:199], v[130:133], v[46:49], v[14:17]
	ds_read_b128 v[130:133], v246 offset:4096
	v_exp_f32_e32 v181, v169
	v_exp_f32_e32 v169, v182
	v_exp_f32_e32 v182, v170
	v_exp_f32_e32 v170, v183
	v_exp_f32_e32 v171, v171
	v_exp_f32_e32 v177, v174
	v_cvt_pk_bf16_f32 v168, v180, v168
	v_cvt_pk_bf16_f32 v169, v169, v170
	v_cvt_pk_bf16_f32 v170, v213, v181
	v_cvt_pk_bf16_f32 v171, v182, v171
	ds_read_b64 v[180:181], v248 offset:32768
	ds_read_b64 v[182:183], v248 offset:32800
	ds_read_b64 v[212:213], v248 offset:35072
	ds_read_b64 v[214:215], v248 offset:35104
	ds_read_b128 v[172:175], v246 offset:6144
	v_cvt_pk_bf16_f32 v176, v200, v176
	v_cvt_pk_bf16_f32 v177, v177, v201
	s_waitcnt lgkmcnt(5)
	v_mfma_f32_16x16x32_bf16 v[200:203], v[130:133], v[34:37], v[2:5]
	v_exp_f32_e32 v231, v190
	v_exp_f32_e32 v206, v178
	v_exp_f32_e32 v179, v179
	v_mfma_f32_16x16x32_bf16 v[208:211], v[130:133], v[38:41], v[10:13]
	v_exp_f32_e32 v188, v188
	v_mfma_f32_16x16x32_bf16 v[192:195], v[184:187], v[42:45], v[6:9]
	v_exp_f32_e32 v189, v189
	v_exp_f32_e32 v196, v196
	v_cvt_pk_bf16_f32 v178, v204, v205
	v_mfma_f32_16x16x32_bf16 v[184:187], v[184:187], v[46:49], v[14:17]
	v_cvt_pk_bf16_f32 v179, v206, v179
	s_nop 2
	v_exp_f32_e32 v192, v192
	v_exp_f32_e32 v193, v193
	v_mfma_f32_16x16x32_bf16 v[86:89], v[240:243], v[168:171], v[86:89]
	v_exp_f32_e32 v194, v194
	v_exp_f32_e32 v187, v187
	ds_read_b128 v[224:227], v247 offset:4096
	s_waitcnt lgkmcnt(4)
	v_mfma_f32_16x16x32_bf16 v[78:81], v[180:183], v[168:171], v[78:81]
	s_add_i32 s38, s38, 2
	s_addk_i32 s12, 0x80
	v_lshl_add_u64 v[148:149], v[148:149], 0, s[16:17]
	s_waitcnt lgkmcnt(2)
	v_mfma_f32_16x16x32_bf16 v[74:77], v[212:215], v[168:171], v[74:77]
	s_and_b64 vcc, exec, s[0:1]
	v_mfma_f32_16x16x32_bf16 v[70:73], v[216:219], v[168:171], v[70:73]
	v_mfma_f32_16x16x32_bf16 v[62:65], v[220:223], v[168:171], v[62:65]
	v_exp_f32_e32 v169, v191
	v_exp_f32_e32 v171, v195
	v_cvt_pk_bf16_f32 v168, v188, v189
	s_waitcnt lgkmcnt(1)
	v_mfma_f32_16x16x32_bf16 v[204:207], v[172:175], v[34:37], v[2:5]
	v_cvt_pk_bf16_f32 v169, v231, v169
	v_exp_f32_e32 v231, v184
	v_exp_f32_e32 v184, v197
	v_exp_f32_e32 v197, v185
	v_exp_f32_e32 v185, v198
	v_exp_f32_e32 v198, v186
	v_exp_f32_e32 v186, v199
	v_cvt_pk_bf16_f32 v170, v192, v193
	v_cvt_pk_bf16_f32 v171, v194, v171
	v_cvt_pk_bf16_f32 v184, v196, v184
	v_cvt_pk_bf16_f32 v185, v185, v186
	v_cvt_pk_bf16_f32 v186, v231, v197
	v_cvt_pk_bf16_f32 v187, v198, v187
	v_mfma_f32_16x16x32_bf16 v[172:175], v[172:175], v[38:41], v[10:13]
	v_exp_f32_e32 v196, v200
	v_exp_f32_e32 v197, v204
	v_exp_f32_e32 v198, v201
	v_mfma_f32_16x16x32_bf16 v[122:125], v[180:183], v[176:179], v[122:125]
	v_exp_f32_e32 v200, v207
	v_exp_f32_e32 v199, v203
	v_mfma_f32_16x16x32_bf16 v[102:105], v[180:183], v[168:171], v[102:105]
	v_mfma_f32_16x16x32_bf16 v[58:61], v[180:183], v[184:187], v[58:61]
	v_exp_f32_e32 v182, v205
	v_exp_f32_e32 v183, v206
	v_exp_f32_e32 v181, v202
	v_mfma_f32_16x16x32_bf16 v[126:129], v[240:243], v[176:179], v[126:129]
	v_cvt_pk_bf16_f32 v180, v196, v198
	v_cvt_pk_bf16_f32 v182, v197, v182
	v_cvt_pk_bf16_f32 v183, v183, v200
	v_mfma_f32_16x16x32_bf16 v[118:121], v[212:215], v[176:179], v[118:121]
	v_exp_f32_e32 v196, v208
	v_exp_f32_e32 v197, v172
	v_exp_f32_e32 v172, v209
	v_mfma_f32_16x16x32_bf16 v[110:113], v[216:219], v[176:179], v[110:113]
	v_exp_f32_e32 v200, v174
	v_cvt_pk_bf16_f32 v181, v181, v199
	v_exp_f32_e32 v198, v173
	v_mfma_f32_16x16x32_bf16 v[106:109], v[220:223], v[176:179], v[106:109]
	ds_read_b128 v[176:179], v247 offset:6144
	v_exp_f32_e32 v199, v210
	ds_read_b128 v[204:207], v246 offset:14336
	v_mfma_f32_16x16x32_bf16 v[114:117], v[240:243], v[168:171], v[114:117]
	v_mfma_f32_16x16x32_bf16 v[98:101], v[212:215], v[168:171], v[98:101]
	v_mfma_f32_16x16x32_bf16 v[94:97], v[216:219], v[168:171], v[94:97]
	v_mfma_f32_16x16x32_bf16 v[90:93], v[220:223], v[168:171], v[90:93]
	v_exp_f32_e32 v171, v175
	v_exp_f32_e32 v169, v211
	v_cvt_pk_bf16_f32 v168, v196, v172
	v_mfma_f32_16x16x32_bf16 v[82:85], v[240:243], v[184:187], v[82:85]
	v_cvt_pk_bf16_f32 v171, v200, v171
	v_mfma_f32_16x16x32_bf16 v[54:57], v[212:215], v[184:187], v[54:57]
	ds_read_b64 v[172:173], v248 offset:32832
	ds_read_b64 v[174:175], v248 offset:32864
	v_cvt_pk_bf16_f32 v169, v199, v169
	v_mfma_f32_16x16x32_bf16 v[50:53], v[216:219], v[184:187], v[50:53]
	v_cvt_pk_bf16_f32 v170, v197, v198
	ds_read_b64 v[196:197], v248 offset:37440
	ds_read_b64 v[198:199], v248 offset:37472
	ds_read_b64 v[200:201], v248 offset:39744
	ds_read_b64 v[202:203], v248 offset:39776
	v_mfma_f32_16x16x32_bf16 v[66:69], v[220:223], v[184:187], v[66:69]
	ds_read_b64 v[184:185], v248 offset:35136
	ds_read_b64 v[186:187], v248 offset:35168
	s_waitcnt lgkmcnt(10)
	v_mfma_f32_16x16x32_bf16 v[188:191], v[224:227], v[42:45], v[6:9]
	ds_read_b64 v[216:217], v248 offset:46592
	ds_read_b64 v[218:219], v248 offset:46624
	s_waitcnt lgkmcnt(11)
	v_mfma_f32_16x16x32_bf16 v[192:195], v[176:179], v[42:45], v[6:9]
	ds_read_b64 v[220:221], v248 offset:48896
	ds_read_b64 v[222:223], v248 offset:48928
	s_nop 1
	v_exp_f32_e32 v188, v188
	v_exp_f32_e32 v189, v189
	v_mfma_f32_16x16x32_bf16 v[224:227], v[224:227], v[46:49], v[14:17]
	v_exp_f32_e32 v190, v190
	s_nop 0
	v_exp_f32_e32 v192, v192
	v_exp_f32_e32 v193, v193
	v_mfma_f32_16x16x32_bf16 v[176:179], v[176:179], v[46:49], v[14:17]
	v_exp_f32_e32 v191, v191
	v_exp_f32_e32 v194, v194
	v_exp_f32_e32 v195, v195
	v_mfma_f32_16x16x32_bf16 v[126:129], v[240:243], v[180:183], v[126:129]
	v_cvt_pk_bf16_f32 v188, v188, v189
	v_cvt_pk_bf16_f32 v189, v190, v191
	v_cvt_pk_bf16_f32 v190, v192, v193
	v_mfma_f32_16x16x32_bf16 v[86:89], v[240:243], v[168:171], v[86:89]
	v_exp_f32_e32 v192, v224
	v_exp_f32_e32 v176, v176
	v_exp_f32_e32 v193, v225
	s_waitcnt lgkmcnt(10)
	v_mfma_f32_16x16x32_bf16 v[122:125], v[172:175], v[180:183], v[122:125]
	v_exp_f32_e32 v177, v177
	v_exp_f32_e32 v178, v178
	v_cvt_pk_bf16_f32 v191, v194, v195
	v_mfma_f32_16x16x32_bf16 v[78:81], v[172:175], v[168:171], v[78:81]
	s_waitcnt lgkmcnt(4)
	v_mfma_f32_16x16x32_bf16 v[118:121], v[184:187], v[180:183], v[118:121]
	v_mfma_f32_16x16x32_bf16 v[74:77], v[184:187], v[168:171], v[74:77]
	v_mfma_f32_16x16x32_bf16 v[110:113], v[196:199], v[180:183], v[110:113]
	v_mfma_f32_16x16x32_bf16 v[70:73], v[196:199], v[168:171], v[70:73]
	v_mfma_f32_16x16x32_bf16 v[106:109], v[200:203], v[180:183], v[106:109]
	v_exp_f32_e32 v180, v226
	v_mfma_f32_16x16x32_bf16 v[62:65], v[200:203], v[168:171], v[62:65]
	v_exp_f32_e32 v169, v227
	v_exp_f32_e32 v171, v179
	v_cvt_pk_bf16_f32 v168, v192, v193
	v_cvt_pk_bf16_f32 v170, v176, v177
	v_cvt_pk_bf16_f32 v169, v180, v169
	v_cvt_pk_bf16_f32 v171, v178, v171
	v_mfma_f32_16x16x32_bf16 v[102:105], v[172:175], v[188:191], v[102:105]
	ds_read_b128 v[224:227], v247 offset:12288
	v_mfma_f32_16x16x32_bf16 v[82:85], v[240:243], v[168:171], v[82:85]
	v_mfma_f32_16x16x32_bf16 v[58:61], v[172:175], v[168:171], v[58:61]
	ds_read_b128 v[172:175], v246 offset:8192
	v_mfma_f32_16x16x32_bf16 v[54:57], v[184:187], v[168:171], v[54:57]
	v_mfma_f32_16x16x32_bf16 v[50:53], v[196:199], v[168:171], v[50:53]
	v_mfma_f32_16x16x32_bf16 v[66:69], v[200:203], v[168:171], v[66:69]
	ds_read_b128 v[168:171], v246 offset:10240
	s_waitcnt lgkmcnt(1)
	v_mfma_f32_16x16x32_bf16 v[176:179], v[172:175], v[34:37], v[2:5]
	s_waitcnt lgkmcnt(0)
	v_mfma_f32_16x16x32_bf16 v[180:183], v[168:171], v[34:37], v[2:5]
	s_nop 5
	v_exp_f32_e32 v176, v176
	v_mfma_f32_16x16x32_bf16 v[172:175], v[172:175], v[38:41], v[10:13]
	v_exp_f32_e32 v208, v180
	v_exp_f32_e32 v177, v177
	v_exp_f32_e32 v209, v181
	v_mfma_f32_16x16x32_bf16 v[168:171], v[168:171], v[38:41], v[10:13]
	v_exp_f32_e32 v178, v178
	s_nop 2
	v_exp_f32_e32 v172, v172
	v_exp_f32_e32 v210, v182
	v_mfma_f32_16x16x32_bf16 v[114:117], v[240:243], v[188:191], v[114:117]
	v_exp_f32_e32 v179, v179
	v_exp_f32_e32 v213, v168
	v_exp_f32_e32 v168, v173
	v_exp_f32_e32 v173, v169
	v_exp_f32_e32 v169, v174
	v_exp_f32_e32 v174, v170
	v_exp_f32_e32 v170, v175
	v_exp_f32_e32 v171, v171
	v_mfma_f32_16x16x32_bf16 v[98:101], v[184:187], v[188:191], v[98:101]
	ds_read_b128 v[184:187], v247 offset:8192
	v_cvt_pk_bf16_f32 v168, v172, v168
	v_cvt_pk_bf16_f32 v169, v169, v170
	v_mfma_f32_16x16x32_bf16 v[94:97], v[196:199], v[188:191], v[94:97]
	v_cvt_pk_bf16_f32 v170, v213, v173
	v_cvt_pk_bf16_f32 v171, v174, v171
	ds_read_b64 v[172:173], v248 offset:41984
	ds_read_b64 v[174:175], v248 offset:42016
	v_mfma_f32_16x16x32_bf16 v[90:93], v[200:203], v[188:191], v[90:93]
	ds_read_b128 v[188:191], v247 offset:10240
	ds_read_b64 v[212:213], v248 offset:44288
	ds_read_b64 v[214:215], v248 offset:44320
	ds_read_b128 v[200:203], v246 offset:12288
	s_waitcnt lgkmcnt(6)
	v_mfma_f32_16x16x32_bf16 v[192:195], v[184:187], v[42:45], v[6:9]
	v_exp_f32_e32 v211, v183
	v_cvt_pk_bf16_f32 v176, v176, v177
	v_cvt_pk_bf16_f32 v177, v178, v179
	s_waitcnt lgkmcnt(3)
	v_mfma_f32_16x16x32_bf16 v[196:199], v[188:191], v[42:45], v[6:9]
	v_cvt_pk_bf16_f32 v178, v208, v209
	s_nop 1
	v_exp_f32_e32 v192, v192
	v_exp_f32_e32 v193, v193
	v_mfma_f32_16x16x32_bf16 v[184:187], v[184:187], v[46:49], v[14:17]
	s_nop 1
	v_exp_f32_e32 v196, v196
	v_exp_f32_e32 v197, v197
	v_exp_f32_e32 v228, v194
	v_mfma_f32_16x16x32_bf16 v[188:191], v[188:191], v[46:49], v[14:17]
	v_exp_f32_e32 v198, v198
	s_nop 0
	v_exp_f32_e32 v184, v184
	v_exp_f32_e32 v185, v185
	v_mfma_f32_16x16x32_bf16 v[86:89], v[240:243], v[168:171], v[86:89]
	v_exp_f32_e32 v186, v186
	s_nop 1
	v_exp_f32_e32 v188, v188
	v_exp_f32_e32 v189, v189
	v_mfma_f32_16x16x32_bf16 v[78:81], v[172:175], v[168:171], v[78:81]
	v_exp_f32_e32 v190, v190
	v_exp_f32_e32 v187, v187
	v_exp_f32_e32 v191, v191
	s_waitcnt lgkmcnt(1)
	v_mfma_f32_16x16x32_bf16 v[74:77], v[212:215], v[168:171], v[74:77]
	v_cvt_pk_bf16_f32 v179, v210, v211
	v_cvt_pk_bf16_f32 v184, v184, v185
	v_cvt_pk_bf16_f32 v185, v186, v187
	v_mfma_f32_16x16x32_bf16 v[70:73], v[216:219], v[168:171], v[70:73]
	v_cvt_pk_bf16_f32 v186, v188, v189
	v_cvt_pk_bf16_f32 v187, v190, v191
	v_mfma_f32_16x16x32_bf16 v[62:65], v[220:223], v[168:171], v[62:65]
	v_exp_f32_e32 v169, v195
	v_exp_f32_e32 v171, v199
	v_cvt_pk_bf16_f32 v168, v192, v193
	s_waitcnt lgkmcnt(0)
	v_mfma_f32_16x16x32_bf16 v[180:183], v[200:203], v[34:37], v[2:5]
	v_cvt_pk_bf16_f32 v169, v228, v169
	v_cvt_pk_bf16_f32 v170, v196, v197
	v_cvt_pk_bf16_f32 v171, v198, v171
	v_mfma_f32_16x16x32_bf16 v[208:211], v[204:207], v[34:37], v[2:5]
	v_mfma_f32_16x16x32_bf16 v[200:203], v[200:203], v[38:41], v[10:13]
	s_nop 2
	v_exp_f32_e32 v180, v180
	s_nop 2
	v_exp_f32_e32 v188, v208
	v_mfma_f32_16x16x32_bf16 v[204:207], v[204:207], v[38:41], v[10:13]
	v_mfma_f32_16x16x32_bf16 v[122:125], v[172:175], v[176:179], v[122:125]
	v_exp_f32_e32 v190, v202
	s_nop 5
	v_exp_f32_e32 v189, v205
	v_exp_f32_e32 v191, v207
	v_mfma_f32_16x16x32_bf16 v[102:105], v[172:175], v[168:171], v[102:105]
	v_mfma_f32_16x16x32_bf16 v[58:61], v[172:175], v[184:187], v[58:61]
	v_exp_f32_e32 v172, v181
	v_exp_f32_e32 v174, v209
	v_exp_f32_e32 v173, v182
	v_exp_f32_e32 v181, v183
	v_mfma_f32_16x16x32_bf16 v[126:129], v[240:243], v[176:179], v[126:129]
	v_exp_f32_e32 v175, v210
	v_exp_f32_e32 v182, v211
	v_cvt_pk_bf16_f32 v172, v180, v172
	v_mfma_f32_16x16x32_bf16 v[118:121], v[212:215], v[176:179], v[118:121]
	v_cvt_pk_bf16_f32 v173, v173, v181
	v_cvt_pk_bf16_f32 v174, v188, v174
	v_exp_f32_e32 v180, v200
	v_mfma_f32_16x16x32_bf16 v[110:113], v[216:219], v[176:179], v[110:113]
	v_exp_f32_e32 v188, v204
	v_exp_f32_e32 v181, v201
	v_cvt_pk_bf16_f32 v175, v175, v182
	v_mfma_f32_16x16x32_bf16 v[106:109], v[220:223], v[176:179], v[106:109]
	ds_read_b128 v[176:179], v247 offset:14336
	v_mfma_f32_16x16x32_bf16 v[114:117], v[240:243], v[168:171], v[114:117]
	v_mfma_f32_16x16x32_bf16 v[98:101], v[212:215], v[168:171], v[98:101]
	v_mfma_f32_16x16x32_bf16 v[94:97], v[216:219], v[168:171], v[94:97]
	v_mfma_f32_16x16x32_bf16 v[90:93], v[220:223], v[168:171], v[90:93]
	v_exp_f32_e32 v171, v206
	v_exp_f32_e32 v169, v203
	v_mfma_f32_16x16x32_bf16 v[82:85], v[240:243], v[184:187], v[82:85]
	v_cvt_pk_bf16_f32 v168, v180, v181
	ds_read_b64 v[180:181], v248 offset:42048
	ds_read_b64 v[182:183], v248 offset:42080
	v_cvt_pk_bf16_f32 v170, v188, v189
	v_mfma_f32_16x16x32_bf16 v[54:57], v[212:215], v[184:187], v[54:57]
	v_cvt_pk_bf16_f32 v169, v190, v169
	v_cvt_pk_bf16_f32 v171, v171, v191
	v_mfma_f32_16x16x32_bf16 v[50:53], v[216:219], v[184:187], v[50:53]
	ds_read_b64 v[188:189], v248 offset:46656
	ds_read_b64 v[190:191], v248 offset:46688
	ds_read_b64 v[200:201], v248 offset:48960
	ds_read_b64 v[202:203], v248 offset:48992
	v_mfma_f32_16x16x32_bf16 v[66:69], v[220:223], v[184:187], v[66:69]
	ds_read_b64 v[184:185], v248 offset:44352
	ds_read_b64 v[186:187], v248 offset:44384
	v_mfma_f32_16x16x32_bf16 v[192:195], v[224:227], v[42:45], v[6:9]
	s_waitcnt lgkmcnt(8)
	v_mfma_f32_16x16x32_bf16 v[196:199], v[176:179], v[42:45], v[6:9]
	v_mfma_f32_16x16x32_bf16 v[224:227], v[224:227], v[46:49], v[14:17]
	s_nop 4
	v_exp_f32_e32 v192, v192
	s_nop 0
	v_exp_f32_e32 v196, v196
	v_exp_f32_e32 v193, v193
	v_mfma_f32_16x16x32_bf16 v[176:179], v[176:179], v[46:49], v[14:17]
	v_exp_f32_e32 v197, v197
	v_exp_f32_e32 v194, v194
	v_exp_f32_e32 v195, v195
	v_mfma_f32_16x16x32_bf16 v[126:129], v[240:243], v[172:175], v[126:129]
	v_exp_f32_e32 v198, v198
	v_exp_f32_e32 v199, v199
	v_cvt_pk_bf16_f32 v192, v192, v193
	v_mfma_f32_16x16x32_bf16 v[86:89], v[240:243], v[168:171], v[86:89]
	v_cvt_pk_bf16_f32 v193, v194, v195
	v_cvt_pk_bf16_f32 v194, v196, v197
	v_exp_f32_e32 v196, v224
	s_waitcnt lgkmcnt(6)
	v_mfma_f32_16x16x32_bf16 v[122:125], v[180:183], v[172:175], v[122:125]
	v_exp_f32_e32 v176, v176
	v_exp_f32_e32 v197, v225
	v_cvt_pk_bf16_f32 v195, v198, v199
	v_mfma_f32_16x16x32_bf16 v[78:81], v[180:183], v[168:171], v[78:81]
	s_waitcnt lgkmcnt(0)
	s_waitcnt vmcnt(3)
	ds_write_b128 v244, v[18:21]
	s_waitcnt vmcnt(1)
	ds_write_b128 v245, v[22:25] offset:32768
	s_waitcnt vmcnt(1)
	ds_write_b128 v244, v[26:29] offset:8192
	s_waitcnt vmcnt(0)
	ds_write_b128 v245, v[30:33] offset:41984
	v_mfma_f32_16x16x32_bf16 v[118:121], v[184:187], v[172:175], v[118:121]
	v_mfma_f32_16x16x32_bf16 v[74:77], v[184:187], v[168:171], v[74:77]
	v_mfma_f32_16x16x32_bf16 v[110:113], v[188:191], v[172:175], v[110:113]
	v_mfma_f32_16x16x32_bf16 v[70:73], v[188:191], v[168:171], v[70:73]
	v_mfma_f32_16x16x32_bf16 v[106:109], v[200:203], v[172:175], v[106:109]
	v_exp_f32_e32 v172, v177
	v_exp_f32_e32 v173, v226
	v_exp_f32_e32 v174, v178
	v_mfma_f32_16x16x32_bf16 v[62:65], v[200:203], v[168:171], v[62:65]
	v_exp_f32_e32 v169, v227
	v_exp_f32_e32 v171, v179
	v_cvt_pk_bf16_f32 v168, v196, v197
	v_cvt_pk_bf16_f32 v170, v176, v172
	v_cvt_pk_bf16_f32 v169, v173, v169
	v_cvt_pk_bf16_f32 v171, v174, v171
	v_mfma_f32_16x16x32_bf16 v[114:117], v[240:243], v[192:195], v[114:117]
	s_nop 0
	v_mfma_f32_16x16x32_bf16 v[82:85], v[240:243], v[168:171], v[82:85]
	v_mfma_f32_16x16x32_bf16 v[102:105], v[180:183], v[192:195], v[102:105]
	v_mfma_f32_16x16x32_bf16 v[58:61], v[180:183], v[168:171], v[58:61]
	v_mfma_f32_16x16x32_bf16 v[98:101], v[184:187], v[192:195], v[98:101]
	v_mfma_f32_16x16x32_bf16 v[54:57], v[184:187], v[168:171], v[54:57]
	v_mfma_f32_16x16x32_bf16 v[94:97], v[188:191], v[192:195], v[94:97]
	v_mfma_f32_16x16x32_bf16 v[50:53], v[188:191], v[168:171], v[50:53]
	v_mfma_f32_16x16x32_bf16 v[90:93], v[200:203], v[192:195], v[90:93]
	v_mfma_f32_16x16x32_bf16 v[66:69], v[200:203], v[168:171], v[66:69]
	v_xor_b32_e32 v246, 0x4000, v246
	v_xor_b32_e32 v247, 0x4000, v247
	v_xor_b32_e32 v244, 0x4000, v244
	v_add_u32_e32 v248, s99, v248
	v_subrev_u32_e32 v245, s99, v245
	s_sub_i32 s99, 0, s99
	s_cbranch_vccnz .LBB0_928
.LBB0_926:
	s_and_b32 s0, s12, 0x80
	s_lshl_b32 s1, s0, 7
	s_add_i32 s39, s1, 0
	s_lshl_b32 s0, s0, 4
	s_add_i32 s2, s39, s0
	s_cmpk_gt_u32 s38, 0x101
	s_cselect_b64 s[0:1], -1, 0
	s_and_b64 vcc, exec, s[0:1]
	s_waitcnt lgkmcnt(0)
	s_barrier
	ds_read_b128 v[130:133], v246
	ds_read_b128 v[168:171], v246 offset:2048
	s_cbranch_vccnz .LBB0_925
	s_cmp_eq_u32 s12, 0
	s_cbranch_scc0 .Lpf_next_925
	v_add_u32_e32 v250, s36, v161
	v_mad_i64_i32 v[250:251], s[40:41], v250, s21, v[146:147]
	v_add_u32_e32 v252, s37, v161
	v_mad_i64_i32 v[252:253], s[40:41], v252, s21, v[146:147]
	s_sub_i32 s100, s35, s36
	s_mul_hi_i32 s101, s100, 0x1640
	s_mul_i32 s100, s100, 0x1640
	s_branch .Lpf_load_925

.Lnoprio_2159:
	s_movk_i32 s99, 0x4800
	v_lshlrev_b32_e32 v134, 1, v158
	s_barrier
	s_waitcnt vmcnt(3)
	ds_write_b128 v244, v[18:21]
	s_waitcnt vmcnt(1)
	ds_write_b128 v245, v[22:25] offset:32768
	s_waitcnt vmcnt(1)
	ds_write_b128 v244, v[26:29] offset:8192
	s_waitcnt vmcnt(0)
	ds_write_b128 v245, v[30:33] offset:41984
	v_xor_b32_e32 v244, 0x4000, v244
	v_add_u32_e32 v245, 0x4800, v245
	s_branch .LBB0_2160
.LBB0_2159:
	s_waitcnt lgkmcnt(1)
	v_mfma_f32_16x16x32_bf16 v[170:173], v[130:133], v[34:37], v[2:5]
	ds_read_b128 v[182:185], v247 offset:2048
	v_mfma_f32_16x16x32_bf16 v[178:181], v[130:133], v[38:41], v[10:13]
	ds_read_b128 v[130:133], v247
	s_nop 2
	s_nop 1
	v_exp_f32_e32 v198, v170
	v_exp_f32_e32 v199, v173
	s_waitcnt lgkmcnt(2)
	v_mfma_f32_16x16x32_bf16 v[174:177], v[166:169], v[34:37], v[2:5]
	v_exp_f32_e32 v178, v178
	ds_read_b64 v[214:215], v248 offset:37376
	ds_read_b64 v[216:217], v248 offset:37408
	v_mfma_f32_16x16x32_bf16 v[166:169], v[166:169], v[38:41], v[10:13]
	ds_read_b64 v[218:219], v248 offset:39680
	ds_read_b64 v[220:221], v248 offset:39712
	s_nop 2
	v_exp_f32_e32 v202, v174
	v_exp_f32_e32 v174, v171
	s_waitcnt lgkmcnt(4)
	v_mfma_f32_16x16x32_bf16 v[186:189], v[130:133], v[42:45], v[6:9]
	v_exp_f32_e32 v203, v175
	v_exp_f32_e32 v211, v166
	v_exp_f32_e32 v166, v179
	v_mfma_f32_16x16x32_bf16 v[194:197], v[130:133], v[46:49], v[14:17]
	ds_read_b128 v[130:133], v246 offset:4096
	v_exp_f32_e32 v179, v167
	v_exp_f32_e32 v167, v180
	v_exp_f32_e32 v180, v168
	v_exp_f32_e32 v168, v181
	v_exp_f32_e32 v169, v169
	v_exp_f32_e32 v175, v172
	v_cvt_pk_bf16_f32 v166, v178, v166
	v_cvt_pk_bf16_f32 v167, v167, v168
	v_cvt_pk_bf16_f32 v168, v211, v179
	v_cvt_pk_bf16_f32 v169, v180, v169
	ds_read_b64 v[178:179], v248 offset:32768
	ds_read_b64 v[180:181], v248 offset:32800
	ds_read_b64 v[210:211], v248 offset:35072
	ds_read_b64 v[212:213], v248 offset:35104
	ds_read_b128 v[170:173], v246 offset:6144
	v_cvt_pk_bf16_f32 v174, v198, v174
	v_cvt_pk_bf16_f32 v175, v175, v199
	s_waitcnt lgkmcnt(5)
	v_mfma_f32_16x16x32_bf16 v[198:201], v[130:133], v[34:37], v[2:5]
	v_exp_f32_e32 v229, v188
	v_exp_f32_e32 v204, v176
	v_exp_f32_e32 v177, v177
	v_mfma_f32_16x16x32_bf16 v[206:209], v[130:133], v[38:41], v[10:13]
	v_exp_f32_e32 v186, v186
	v_mfma_f32_16x16x32_bf16 v[190:193], v[182:185], v[42:45], v[6:9]
	v_exp_f32_e32 v187, v187
	v_exp_f32_e32 v194, v194
	v_cvt_pk_bf16_f32 v176, v202, v203
	v_mfma_f32_16x16x32_bf16 v[182:185], v[182:185], v[46:49], v[14:17]
	v_cvt_pk_bf16_f32 v177, v204, v177
	s_nop 2
	v_exp_f32_e32 v190, v190
	v_exp_f32_e32 v191, v191
	v_mfma_f32_16x16x32_bf16 v[86:89], v[240:243], v[166:169], v[86:89]
	v_exp_f32_e32 v192, v192
	v_exp_f32_e32 v185, v185
	ds_read_b128 v[222:225], v247 offset:4096
	s_waitcnt lgkmcnt(4)
	v_mfma_f32_16x16x32_bf16 v[78:81], v[178:181], v[166:169], v[78:81]
	s_add_i32 s36, s36, 2
	s_addk_i32 s10, 0x80
	v_lshl_add_u64 v[146:147], v[146:147], 0, s[14:15]
	s_waitcnt lgkmcnt(2)
	v_mfma_f32_16x16x32_bf16 v[74:77], v[210:213], v[166:169], v[74:77]
	s_and_b64 vcc, exec, s[0:1]
	v_mfma_f32_16x16x32_bf16 v[70:73], v[214:217], v[166:169], v[70:73]
	v_mfma_f32_16x16x32_bf16 v[62:65], v[218:221], v[166:169], v[62:65]
	v_exp_f32_e32 v167, v189
	v_exp_f32_e32 v169, v193
	v_cvt_pk_bf16_f32 v166, v186, v187
	s_waitcnt lgkmcnt(1)
	v_mfma_f32_16x16x32_bf16 v[202:205], v[170:173], v[34:37], v[2:5]
	v_cvt_pk_bf16_f32 v167, v229, v167
	v_exp_f32_e32 v229, v182
	v_exp_f32_e32 v182, v195
	v_exp_f32_e32 v195, v183
	v_exp_f32_e32 v183, v196
	v_exp_f32_e32 v196, v184
	v_exp_f32_e32 v184, v197
	v_cvt_pk_bf16_f32 v168, v190, v191
	v_cvt_pk_bf16_f32 v169, v192, v169
	v_cvt_pk_bf16_f32 v182, v194, v182
	v_cvt_pk_bf16_f32 v183, v183, v184
	v_cvt_pk_bf16_f32 v184, v229, v195
	v_cvt_pk_bf16_f32 v185, v196, v185
	v_mfma_f32_16x16x32_bf16 v[170:173], v[170:173], v[38:41], v[10:13]
	v_exp_f32_e32 v194, v198
	v_exp_f32_e32 v195, v202
	v_exp_f32_e32 v196, v199
	v_mfma_f32_16x16x32_bf16 v[122:125], v[178:181], v[174:177], v[122:125]
	v_exp_f32_e32 v198, v205
	v_exp_f32_e32 v197, v201
	v_mfma_f32_16x16x32_bf16 v[102:105], v[178:181], v[166:169], v[102:105]
	v_mfma_f32_16x16x32_bf16 v[58:61], v[178:181], v[182:185], v[58:61]
	v_exp_f32_e32 v180, v203
	v_exp_f32_e32 v181, v204
	v_exp_f32_e32 v179, v200
	v_mfma_f32_16x16x32_bf16 v[126:129], v[240:243], v[174:177], v[126:129]
	v_cvt_pk_bf16_f32 v178, v194, v196
	v_cvt_pk_bf16_f32 v180, v195, v180
	v_cvt_pk_bf16_f32 v181, v181, v198
	v_mfma_f32_16x16x32_bf16 v[118:121], v[210:213], v[174:177], v[118:121]
	v_exp_f32_e32 v194, v206
	v_exp_f32_e32 v195, v170
	v_exp_f32_e32 v170, v207
	v_mfma_f32_16x16x32_bf16 v[110:113], v[214:217], v[174:177], v[110:113]
	v_exp_f32_e32 v198, v172
	v_cvt_pk_bf16_f32 v179, v179, v197
	v_exp_f32_e32 v196, v171
	v_mfma_f32_16x16x32_bf16 v[106:109], v[218:221], v[174:177], v[106:109]
	ds_read_b128 v[174:177], v247 offset:6144
	v_exp_f32_e32 v197, v208
	ds_read_b128 v[202:205], v246 offset:14336
	v_mfma_f32_16x16x32_bf16 v[114:117], v[240:243], v[166:169], v[114:117]
	v_mfma_f32_16x16x32_bf16 v[98:101], v[210:213], v[166:169], v[98:101]
	v_mfma_f32_16x16x32_bf16 v[94:97], v[214:217], v[166:169], v[94:97]
	v_mfma_f32_16x16x32_bf16 v[90:93], v[218:221], v[166:169], v[90:93]
	v_exp_f32_e32 v169, v173
	v_exp_f32_e32 v167, v209
	v_cvt_pk_bf16_f32 v166, v194, v170
	v_mfma_f32_16x16x32_bf16 v[82:85], v[240:243], v[182:185], v[82:85]
	v_cvt_pk_bf16_f32 v169, v198, v169
	v_mfma_f32_16x16x32_bf16 v[54:57], v[210:213], v[182:185], v[54:57]
	ds_read_b64 v[170:171], v248 offset:32832
	ds_read_b64 v[172:173], v248 offset:32864
	v_cvt_pk_bf16_f32 v167, v197, v167
	v_mfma_f32_16x16x32_bf16 v[50:53], v[214:217], v[182:185], v[50:53]
	v_cvt_pk_bf16_f32 v168, v195, v196
	ds_read_b64 v[194:195], v248 offset:37440
	ds_read_b64 v[196:197], v248 offset:37472
	ds_read_b64 v[198:199], v248 offset:39744
	ds_read_b64 v[200:201], v248 offset:39776
	v_mfma_f32_16x16x32_bf16 v[66:69], v[218:221], v[182:185], v[66:69]
	ds_read_b64 v[182:183], v248 offset:35136
	ds_read_b64 v[184:185], v248 offset:35168
	s_waitcnt lgkmcnt(10)
	v_mfma_f32_16x16x32_bf16 v[186:189], v[222:225], v[42:45], v[6:9]
	ds_read_b64 v[214:215], v248 offset:46592
	ds_read_b64 v[216:217], v248 offset:46624
	s_waitcnt lgkmcnt(11)
	v_mfma_f32_16x16x32_bf16 v[190:193], v[174:177], v[42:45], v[6:9]
	ds_read_b64 v[218:219], v248 offset:48896
	ds_read_b64 v[220:221], v248 offset:48928
	s_nop 1
	v_exp_f32_e32 v186, v186
	v_exp_f32_e32 v187, v187
	v_mfma_f32_16x16x32_bf16 v[222:225], v[222:225], v[46:49], v[14:17]
	v_exp_f32_e32 v188, v188
	s_nop 0
	v_exp_f32_e32 v190, v190
	v_exp_f32_e32 v191, v191
	v_mfma_f32_16x16x32_bf16 v[174:177], v[174:177], v[46:49], v[14:17]
	v_exp_f32_e32 v189, v189
	v_exp_f32_e32 v192, v192
	v_exp_f32_e32 v193, v193
	v_mfma_f32_16x16x32_bf16 v[126:129], v[240:243], v[178:181], v[126:129]
	v_cvt_pk_bf16_f32 v186, v186, v187
	v_cvt_pk_bf16_f32 v187, v188, v189
	v_cvt_pk_bf16_f32 v188, v190, v191
	v_mfma_f32_16x16x32_bf16 v[86:89], v[240:243], v[166:169], v[86:89]
	v_exp_f32_e32 v190, v222
	v_exp_f32_e32 v174, v174
	v_exp_f32_e32 v191, v223
	s_waitcnt lgkmcnt(10)
	v_mfma_f32_16x16x32_bf16 v[122:125], v[170:173], v[178:181], v[122:125]
	v_exp_f32_e32 v175, v175
	v_exp_f32_e32 v176, v176
	v_cvt_pk_bf16_f32 v189, v192, v193
	v_mfma_f32_16x16x32_bf16 v[78:81], v[170:173], v[166:169], v[78:81]
	s_waitcnt lgkmcnt(4)
	v_mfma_f32_16x16x32_bf16 v[118:121], v[182:185], v[178:181], v[118:121]
	v_mfma_f32_16x16x32_bf16 v[74:77], v[182:185], v[166:169], v[74:77]
	v_mfma_f32_16x16x32_bf16 v[110:113], v[194:197], v[178:181], v[110:113]
	v_mfma_f32_16x16x32_bf16 v[70:73], v[194:197], v[166:169], v[70:73]
	v_mfma_f32_16x16x32_bf16 v[106:109], v[198:201], v[178:181], v[106:109]
	v_exp_f32_e32 v178, v224
	v_mfma_f32_16x16x32_bf16 v[62:65], v[198:201], v[166:169], v[62:65]
	v_exp_f32_e32 v167, v225
	v_exp_f32_e32 v169, v177
	v_cvt_pk_bf16_f32 v166, v190, v191
	v_cvt_pk_bf16_f32 v168, v174, v175
	v_cvt_pk_bf16_f32 v167, v178, v167
	v_cvt_pk_bf16_f32 v169, v176, v169
	v_mfma_f32_16x16x32_bf16 v[102:105], v[170:173], v[186:189], v[102:105]
	ds_read_b128 v[222:225], v247 offset:12288
	v_mfma_f32_16x16x32_bf16 v[82:85], v[240:243], v[166:169], v[82:85]
	v_mfma_f32_16x16x32_bf16 v[58:61], v[170:173], v[166:169], v[58:61]
	ds_read_b128 v[170:173], v246 offset:8192
	v_mfma_f32_16x16x32_bf16 v[54:57], v[182:185], v[166:169], v[54:57]
	v_mfma_f32_16x16x32_bf16 v[50:53], v[194:197], v[166:169], v[50:53]
	v_mfma_f32_16x16x32_bf16 v[66:69], v[198:201], v[166:169], v[66:69]
	ds_read_b128 v[166:169], v246 offset:10240
	s_waitcnt lgkmcnt(1)
	v_mfma_f32_16x16x32_bf16 v[174:177], v[170:173], v[34:37], v[2:5]
	s_waitcnt lgkmcnt(0)
	v_mfma_f32_16x16x32_bf16 v[178:181], v[166:169], v[34:37], v[2:5]
	s_nop 5
	v_exp_f32_e32 v174, v174
	v_mfma_f32_16x16x32_bf16 v[170:173], v[170:173], v[38:41], v[10:13]
	v_exp_f32_e32 v206, v178
	v_exp_f32_e32 v175, v175
	v_exp_f32_e32 v207, v179
	v_mfma_f32_16x16x32_bf16 v[166:169], v[166:169], v[38:41], v[10:13]
	v_exp_f32_e32 v176, v176
	s_nop 2
	v_exp_f32_e32 v170, v170
	v_exp_f32_e32 v208, v180
	v_mfma_f32_16x16x32_bf16 v[114:117], v[240:243], v[186:189], v[114:117]
	v_exp_f32_e32 v177, v177
	v_exp_f32_e32 v211, v166
	v_exp_f32_e32 v166, v171
	v_exp_f32_e32 v171, v167
	v_exp_f32_e32 v167, v172
	v_exp_f32_e32 v172, v168
	v_exp_f32_e32 v168, v173
	v_exp_f32_e32 v169, v169
	v_mfma_f32_16x16x32_bf16 v[98:101], v[182:185], v[186:189], v[98:101]
	ds_read_b128 v[182:185], v247 offset:8192
	v_cvt_pk_bf16_f32 v166, v170, v166
	v_cvt_pk_bf16_f32 v167, v167, v168
	v_mfma_f32_16x16x32_bf16 v[94:97], v[194:197], v[186:189], v[94:97]
	v_cvt_pk_bf16_f32 v168, v211, v171
	v_cvt_pk_bf16_f32 v169, v172, v169
	ds_read_b64 v[170:171], v248 offset:41984
	ds_read_b64 v[172:173], v248 offset:42016
	v_mfma_f32_16x16x32_bf16 v[90:93], v[198:201], v[186:189], v[90:93]
	ds_read_b128 v[186:189], v247 offset:10240
	ds_read_b64 v[210:211], v248 offset:44288
	ds_read_b64 v[212:213], v248 offset:44320
	ds_read_b128 v[198:201], v246 offset:12288
	s_waitcnt lgkmcnt(6)
	v_mfma_f32_16x16x32_bf16 v[190:193], v[182:185], v[42:45], v[6:9]
	v_exp_f32_e32 v209, v181
	v_cvt_pk_bf16_f32 v174, v174, v175
	v_cvt_pk_bf16_f32 v175, v176, v177
	s_waitcnt lgkmcnt(3)
	v_mfma_f32_16x16x32_bf16 v[194:197], v[186:189], v[42:45], v[6:9]
	v_cvt_pk_bf16_f32 v176, v206, v207
	s_nop 1
	v_exp_f32_e32 v190, v190
	v_exp_f32_e32 v191, v191
	v_mfma_f32_16x16x32_bf16 v[182:185], v[182:185], v[46:49], v[14:17]
	s_nop 1
	v_exp_f32_e32 v194, v194
	v_exp_f32_e32 v195, v195
	v_exp_f32_e32 v226, v192
	v_mfma_f32_16x16x32_bf16 v[186:189], v[186:189], v[46:49], v[14:17]
	v_exp_f32_e32 v196, v196
	s_nop 0
	v_exp_f32_e32 v182, v182
	v_exp_f32_e32 v183, v183
	v_mfma_f32_16x16x32_bf16 v[86:89], v[240:243], v[166:169], v[86:89]
	v_exp_f32_e32 v184, v184
	s_nop 1
	v_exp_f32_e32 v186, v186
	v_exp_f32_e32 v187, v187
	v_mfma_f32_16x16x32_bf16 v[78:81], v[170:173], v[166:169], v[78:81]
	v_exp_f32_e32 v188, v188
	v_exp_f32_e32 v185, v185
	v_exp_f32_e32 v189, v189
	s_waitcnt lgkmcnt(1)
	v_mfma_f32_16x16x32_bf16 v[74:77], v[210:213], v[166:169], v[74:77]
	v_cvt_pk_bf16_f32 v177, v208, v209
	v_cvt_pk_bf16_f32 v182, v182, v183
	v_cvt_pk_bf16_f32 v183, v184, v185
	v_mfma_f32_16x16x32_bf16 v[70:73], v[214:217], v[166:169], v[70:73]
	v_cvt_pk_bf16_f32 v184, v186, v187
	v_cvt_pk_bf16_f32 v185, v188, v189
	v_mfma_f32_16x16x32_bf16 v[62:65], v[218:221], v[166:169], v[62:65]
	v_exp_f32_e32 v167, v193
	v_exp_f32_e32 v169, v197
	v_cvt_pk_bf16_f32 v166, v190, v191
	s_waitcnt lgkmcnt(0)
	v_mfma_f32_16x16x32_bf16 v[178:181], v[198:201], v[34:37], v[2:5]
	v_cvt_pk_bf16_f32 v167, v226, v167
	v_cvt_pk_bf16_f32 v168, v194, v195
	v_cvt_pk_bf16_f32 v169, v196, v169
	v_mfma_f32_16x16x32_bf16 v[206:209], v[202:205], v[34:37], v[2:5]
	v_mfma_f32_16x16x32_bf16 v[198:201], v[198:201], v[38:41], v[10:13]
	s_nop 2
	v_exp_f32_e32 v178, v178
	s_nop 2
	v_exp_f32_e32 v186, v206
	v_mfma_f32_16x16x32_bf16 v[202:205], v[202:205], v[38:41], v[10:13]
	v_mfma_f32_16x16x32_bf16 v[122:125], v[170:173], v[174:177], v[122:125]
	v_exp_f32_e32 v188, v200
	s_nop 5
	v_exp_f32_e32 v187, v203
	v_exp_f32_e32 v189, v205
	v_mfma_f32_16x16x32_bf16 v[102:105], v[170:173], v[166:169], v[102:105]
	v_mfma_f32_16x16x32_bf16 v[58:61], v[170:173], v[182:185], v[58:61]
	v_exp_f32_e32 v170, v179
	v_exp_f32_e32 v172, v207
	v_exp_f32_e32 v171, v180
	v_exp_f32_e32 v179, v181
	v_mfma_f32_16x16x32_bf16 v[126:129], v[240:243], v[174:177], v[126:129]
	v_exp_f32_e32 v173, v208
	v_exp_f32_e32 v180, v209
	v_cvt_pk_bf16_f32 v170, v178, v170
	v_mfma_f32_16x16x32_bf16 v[118:121], v[210:213], v[174:177], v[118:121]
	v_cvt_pk_bf16_f32 v171, v171, v179
	v_cvt_pk_bf16_f32 v172, v186, v172
	v_exp_f32_e32 v178, v198
	v_mfma_f32_16x16x32_bf16 v[110:113], v[214:217], v[174:177], v[110:113]
	v_exp_f32_e32 v186, v202
	v_exp_f32_e32 v179, v199
	v_cvt_pk_bf16_f32 v173, v173, v180
	v_mfma_f32_16x16x32_bf16 v[106:109], v[218:221], v[174:177], v[106:109]
	ds_read_b128 v[174:177], v247 offset:14336
	v_mfma_f32_16x16x32_bf16 v[114:117], v[240:243], v[166:169], v[114:117]
	v_mfma_f32_16x16x32_bf16 v[98:101], v[210:213], v[166:169], v[98:101]
	v_mfma_f32_16x16x32_bf16 v[94:97], v[214:217], v[166:169], v[94:97]
	v_mfma_f32_16x16x32_bf16 v[90:93], v[218:221], v[166:169], v[90:93]
	v_exp_f32_e32 v169, v204
	v_exp_f32_e32 v167, v201
	v_mfma_f32_16x16x32_bf16 v[82:85], v[240:243], v[182:185], v[82:85]
	v_cvt_pk_bf16_f32 v166, v178, v179
	ds_read_b64 v[178:179], v248 offset:42048
	ds_read_b64 v[180:181], v248 offset:42080
	v_cvt_pk_bf16_f32 v168, v186, v187
	v_mfma_f32_16x16x32_bf16 v[54:57], v[210:213], v[182:185], v[54:57]
	v_cvt_pk_bf16_f32 v167, v188, v167
	v_cvt_pk_bf16_f32 v169, v169, v189
	v_mfma_f32_16x16x32_bf16 v[50:53], v[214:217], v[182:185], v[50:53]
	ds_read_b64 v[186:187], v248 offset:46656
	ds_read_b64 v[188:189], v248 offset:46688
	ds_read_b64 v[198:199], v248 offset:48960
	ds_read_b64 v[200:201], v248 offset:48992
	v_mfma_f32_16x16x32_bf16 v[66:69], v[218:221], v[182:185], v[66:69]
	ds_read_b64 v[182:183], v248 offset:44352
	ds_read_b64 v[184:185], v248 offset:44384
	v_mfma_f32_16x16x32_bf16 v[190:193], v[222:225], v[42:45], v[6:9]
	s_waitcnt lgkmcnt(8)
	v_mfma_f32_16x16x32_bf16 v[194:197], v[174:177], v[42:45], v[6:9]
	v_mfma_f32_16x16x32_bf16 v[222:225], v[222:225], v[46:49], v[14:17]
	s_nop 4
	v_exp_f32_e32 v190, v190
	s_nop 0
	v_exp_f32_e32 v194, v194
	v_exp_f32_e32 v191, v191
	v_mfma_f32_16x16x32_bf16 v[174:177], v[174:177], v[46:49], v[14:17]
	v_exp_f32_e32 v195, v195
	v_exp_f32_e32 v192, v192
	v_exp_f32_e32 v193, v193
	v_mfma_f32_16x16x32_bf16 v[126:129], v[240:243], v[170:173], v[126:129]
	v_exp_f32_e32 v196, v196
	v_exp_f32_e32 v197, v197
	v_cvt_pk_bf16_f32 v190, v190, v191
	v_mfma_f32_16x16x32_bf16 v[86:89], v[240:243], v[166:169], v[86:89]
	v_cvt_pk_bf16_f32 v191, v192, v193
	v_cvt_pk_bf16_f32 v192, v194, v195
	v_exp_f32_e32 v194, v222
	s_waitcnt lgkmcnt(6)
	v_mfma_f32_16x16x32_bf16 v[122:125], v[178:181], v[170:173], v[122:125]
	v_exp_f32_e32 v174, v174
	v_exp_f32_e32 v195, v223
	v_cvt_pk_bf16_f32 v193, v196, v197
	v_mfma_f32_16x16x32_bf16 v[78:81], v[178:181], v[166:169], v[78:81]
	s_waitcnt lgkmcnt(0)
	s_waitcnt vmcnt(3)
	ds_write_b128 v244, v[18:21]
	s_waitcnt vmcnt(1)
	ds_write_b128 v245, v[22:25] offset:32768
	s_waitcnt vmcnt(1)
	ds_write_b128 v244, v[26:29] offset:8192
	s_waitcnt vmcnt(0)
	ds_write_b128 v245, v[30:33] offset:41984
	v_mfma_f32_16x16x32_bf16 v[118:121], v[182:185], v[170:173], v[118:121]
	v_mfma_f32_16x16x32_bf16 v[74:77], v[182:185], v[166:169], v[74:77]
	v_mfma_f32_16x16x32_bf16 v[110:113], v[186:189], v[170:173], v[110:113]
	v_mfma_f32_16x16x32_bf16 v[70:73], v[186:189], v[166:169], v[70:73]
	v_mfma_f32_16x16x32_bf16 v[106:109], v[198:201], v[170:173], v[106:109]
	v_exp_f32_e32 v170, v175
	v_exp_f32_e32 v171, v224
	v_exp_f32_e32 v172, v176
	v_mfma_f32_16x16x32_bf16 v[62:65], v[198:201], v[166:169], v[62:65]
	v_exp_f32_e32 v167, v225
	v_exp_f32_e32 v169, v177
	v_cvt_pk_bf16_f32 v166, v194, v195
	v_cvt_pk_bf16_f32 v168, v174, v170
	v_cvt_pk_bf16_f32 v167, v171, v167
	v_cvt_pk_bf16_f32 v169, v172, v169
	v_mfma_f32_16x16x32_bf16 v[114:117], v[240:243], v[190:193], v[114:117]
	s_nop 0
	v_mfma_f32_16x16x32_bf16 v[82:85], v[240:243], v[166:169], v[82:85]
	v_mfma_f32_16x16x32_bf16 v[102:105], v[178:181], v[190:193], v[102:105]
	v_mfma_f32_16x16x32_bf16 v[58:61], v[178:181], v[166:169], v[58:61]
	v_mfma_f32_16x16x32_bf16 v[98:101], v[182:185], v[190:193], v[98:101]
	v_mfma_f32_16x16x32_bf16 v[54:57], v[182:185], v[166:169], v[54:57]
	v_mfma_f32_16x16x32_bf16 v[94:97], v[186:189], v[190:193], v[94:97]
	v_mfma_f32_16x16x32_bf16 v[50:53], v[186:189], v[166:169], v[50:53]
	v_mfma_f32_16x16x32_bf16 v[90:93], v[198:201], v[190:193], v[90:93]
	v_mfma_f32_16x16x32_bf16 v[66:69], v[198:201], v[166:169], v[66:69]
	v_xor_b32_e32 v246, 0x4000, v246
	v_xor_b32_e32 v247, 0x4000, v247
	v_xor_b32_e32 v244, 0x4000, v244
	v_add_u32_e32 v248, s99, v248
	v_subrev_u32_e32 v245, s99, v245
	s_sub_i32 s99, 0, s99
	s_cbranch_vccnz .LBB0_2162
.LBB0_2160:
	s_and_b32 s0, s10, 0x80
	s_lshl_b32 s1, s0, 7
	s_add_i32 s37, s1, 0
	s_lshl_b32 s0, s0, 4
	s_add_i32 s2, s37, s0
	s_cmpk_gt_u32 s36, 0x101
	s_cselect_b64 s[0:1], -1, 0
	s_and_b64 vcc, exec, s[0:1]
	s_waitcnt lgkmcnt(0)
	s_barrier
	ds_read_b128 v[130:133], v246
	ds_read_b128 v[166:169], v246 offset:2048
	s_cbranch_vccnz .LBB0_2159
	s_cmp_eq_u32 s10, 0
	s_cbranch_scc0 .Lpf_next_2159
	v_add_u32_e32 v250, s34, v159
	v_mad_i64_i32 v[250:251], s[38:39], v250, s19, v[144:145]
	v_add_u32_e32 v252, s35, v159
	v_mad_i64_i32 v[252:253], s[38:39], v252, s19, v[144:145]
	s_sub_i32 s100, s33, s34
	s_mul_hi_i32 s101, s100, 0x1640
	s_mul_i32 s100, s100, 0x1640
	s_branch .Lpf_load_2159
